# norm0 and final RMSNorm loops: loop-invariant gain loads hoisted out (were reloaded behind vmcnt(0) which stalled each wave on its own stores)
# baseline (speedup 1.0000x reference)
.LBB0_297:
	s_and_b64 vcc, exec, s[16:17]
	s_cbranch_vccz .LBB0_302
	s_cmpk_gt_i32 s20, 0x2fff
	s_cbranch_scc1 .LBB0_301
	v_and_b32_e32 v0, 64, v199
	v_add_u32_e32 v0, 64, v0
	v_xor_b32_e32 v1, 1, v199
	v_cmp_lt_i32_e32 vcc, v1, v0
	s_lshl_b32 s0, s20, 2
	s_ashr_i32 s1, s0, 31
	v_cndmask_b32_e32 v1, v199, v1, vcc
	v_lshlrev_b32_e32 v78, 2, v1
	v_xor_b32_e32 v1, 2, v199
	v_cmp_lt_i32_e32 vcc, v1, v0
	s_lshl_b64 s[2:3], s[0:1], 12
	v_readlane_b32 s4, v245, 1
	v_cndmask_b32_e32 v1, v199, v1, vcc
	v_lshlrev_b32_e32 v79, 2, v1
	v_xor_b32_e32 v1, 4, v199
	v_cmp_lt_i32_e32 vcc, v1, v0
	s_add_u32 s2, s4, s2
	v_readlane_b32 s4, v245, 2
	v_cndmask_b32_e32 v1, v199, v1, vcc
	v_lshlrev_b32_e32 v80, 2, v1
	v_xor_b32_e32 v1, 8, v199
	v_cmp_lt_i32_e32 vcc, v1, v0
	v_lshlrev_b32_e32 v154, 5, v201
	s_addc_u32 s3, s4, s3
	v_cndmask_b32_e32 v1, v199, v1, vcc
	v_lshlrev_b32_e32 v81, 2, v1
	v_xor_b32_e32 v1, 16, v199
	v_cmp_lt_i32_e32 vcc, v1, v0
	v_readlane_b32 s48, v247, 18
	v_lshl_add_u64 v[18:19], s[2:3], 0, v[154:155]
	v_cndmask_b32_e32 v1, v199, v1, vcc
	v_lshlrev_b32_e32 v82, 2, v1
	v_xor_b32_e32 v1, 32, v199
	s_lshl_b64 s[2:3], s[0:1], 11
	v_readlane_b32 s4, v245, 20
	v_cmp_lt_i32_e32 vcc, v1, v0
	v_readlane_b32 s60, v247, 30
	v_readlane_b32 s61, v247, 31
	v_readlane_b32 s5, v245, 21
	s_add_u32 s2, s4, s2
	v_cndmask_b32_e32 v0, v199, v1, vcc
	v_lshl_add_u64 v[16:17], s[60:61], 0, v[154:155]
	v_lshlrev_b32_e32 v154, 4, v201
	s_addc_u32 s3, s5, s3
	v_lshlrev_b32_e32 v83, 2, v0
	v_lshl_add_u64 v[0:1], s[2:3], 0, v[154:155]
	s_mov_b64 s[2:3], 0x5001c00
	v_lshl_add_u64 v[20:21], v[0:1], 0, s[2:3]
	v_readlane_b32 s49, v247, 19
	v_readlane_b32 s50, v247, 20
	v_readlane_b32 s51, v247, 21
	v_readlane_b32 s52, v247, 22
	v_readlane_b32 s53, v247, 23
	v_readlane_b32 s54, v247, 24
	v_readlane_b32 s55, v247, 25
	v_readlane_b32 s56, v247, 26
	v_readlane_b32 s57, v247, 27
	v_readlane_b32 s58, v247, 28
	v_readlane_b32 s59, v247, 29
	v_readlane_b32 s62, v247, 32
	v_readlane_b32 s63, v247, 33
	global_load_dwordx4 v[100:103], v[16:17], off
	global_load_dwordx4 v[104:107], v[16:17], off offset:16
	global_load_dwordx4 v[108:111], v[16:17], off offset:2048
	global_load_dwordx4 v[112:115], v[16:17], off offset:2064
.LBB0_300:
	v_add_co_u32_e32 v0, vcc, 0xfffff000, v20
	s_movk_i32 s1, 0xd000
	s_nop 0
	v_addc_co_u32_e32 v1, vcc, -1, v21, vcc
	global_load_dwordx4 v[22:25], v[0:1], off offset:-3072
	global_load_dwordx4 v[26:29], v[0:1], off offset:-2048
	global_load_dwordx4 v[30:33], v[0:1], off offset:-1024
	global_load_dwordx4 v[84:87], v[20:21], off offset:-4096
	global_load_dwordx4 v[34:37], v[20:21], off offset:-3072
	global_load_dwordx4 v[12:15], v[20:21], off offset:-2048
	global_load_dwordx4 v[62:65], v[20:21], off offset:-1024
	global_load_dwordx4 v[8:11], v[20:21], off
	s_add_i32 s0, s0, s30
	v_lshl_add_u64 v[20:21], v[20:21], 0, s[70:71]
	s_cmp_gt_i32 s0, 0xbfff
	s_waitcnt vmcnt(7)
	v_and_b32_e32 v47, 0xffff0000, v22
	v_lshlrev_b32_e32 v46, 16, v22
	s_waitcnt vmcnt(5)
	v_and_b32_e32 v49, 0xffff0000, v30
	v_lshlrev_b32_e32 v44, 16, v24
	v_and_b32_e32 v45, 0xffff0000, v24
	v_lshlrev_b32_e32 v42, 16, v25
	v_and_b32_e32 v43, 0xffff0000, v25
	v_lshlrev_b32_e32 v48, 16, v30
	v_mov_b32_e32 v24, v49
	v_mov_b32_e32 v25, v47
	v_lshlrev_b32_e32 v40, 16, v23
	v_and_b32_e32 v41, 0xffff0000, v23
	v_mov_b32_e32 v22, v48
	v_mov_b32_e32 v23, v46
	v_pk_mul_f32 v[24:25], v[24:25], v[24:25]
	s_waitcnt vmcnt(3)
	v_and_b32_e32 v73, 0xffff0000, v34
	v_lshlrev_b32_e32 v70, 16, v35
	v_and_b32_e32 v71, 0xffff0000, v35
	s_waitcnt vmcnt(1)
	v_and_b32_e32 v35, 0xffff0000, v62
	v_pk_fma_f32 v[38:39], v[22:23], v[22:23], v[24:25]
	v_lshlrev_b32_e32 v56, 16, v31
	v_lshlrev_b32_e32 v72, 16, v34
	v_lshlrev_b32_e32 v34, 16, v62
	v_mov_b32_e32 v24, v35
	v_mov_b32_e32 v25, v73
	v_and_b32_e32 v57, 0xffff0000, v31
	v_mov_b32_e32 v76, v56
	v_mov_b32_e32 v77, v40
	v_mov_b32_e32 v22, v34
	v_mov_b32_e32 v23, v72
	v_pk_mul_f32 v[24:25], v[24:25], v[24:25]
	v_lshlrev_b32_e32 v52, 16, v32
	v_and_b32_e32 v53, 0xffff0000, v32
	v_lshlrev_b32_e32 v50, 16, v33
	v_and_b32_e32 v51, 0xffff0000, v33
	v_pk_fma_f32 v[60:61], v[22:23], v[22:23], v[24:25]
	v_lshlrev_b32_e32 v32, 16, v64
	v_and_b32_e32 v33, 0xffff0000, v64
	v_lshlrev_b32_e32 v30, 16, v65
	v_and_b32_e32 v31, 0xffff0000, v65
	v_lshlrev_b32_e32 v64, 16, v26
	v_and_b32_e32 v65, 0xffff0000, v26
	v_lshlrev_b32_e32 v74, 16, v27
	v_and_b32_e32 v75, 0xffff0000, v27
	v_lshlrev_b32_e32 v22, 16, v28
	v_and_b32_e32 v23, 0xffff0000, v28
	v_lshlrev_b32_e32 v26, 16, v29
	v_and_b32_e32 v27, 0xffff0000, v29
	v_mov_b32_e32 v28, v57
	v_mov_b32_e32 v29, v41
	v_pk_fma_f32 v[38:39], v[76:77], v[76:77], v[38:39]
	v_mov_b32_e32 v76, v53
	v_pk_fma_f32 v[28:29], v[28:29], v[28:29], v[38:39]
	v_mov_b32_e32 v38, v52
	v_mov_b32_e32 v39, v44
	v_mov_b32_e32 v77, v45
	v_pk_fma_f32 v[28:29], v[38:39], v[38:39], v[28:29]
	v_mov_b32_e32 v38, v50
	v_pk_fma_f32 v[28:29], v[76:77], v[76:77], v[28:29]
	v_mov_b32_e32 v39, v42
	v_lshlrev_b32_e32 v54, 16, v84
	v_mov_b32_e32 v76, v51
	v_mov_b32_e32 v77, v43
	v_pk_fma_f32 v[28:29], v[38:39], v[38:39], v[28:29]
	v_and_b32_e32 v55, 0xffff0000, v84
	v_pk_fma_f32 v[28:29], v[76:77], v[76:77], v[28:29]
	v_mov_b32_e32 v38, v54
	v_mov_b32_e32 v39, v64
	v_lshlrev_b32_e32 v58, 16, v85
	v_mov_b32_e32 v76, v55
	v_mov_b32_e32 v77, v65
	v_pk_fma_f32 v[28:29], v[38:39], v[38:39], v[28:29]
	v_and_b32_e32 v59, 0xffff0000, v85
	v_lshlrev_b32_e32 v24, 16, v86
	v_and_b32_e32 v25, 0xffff0000, v86
	v_pk_fma_f32 v[28:29], v[76:77], v[76:77], v[28:29]
	v_mov_b32_e32 v38, v58
	v_mov_b32_e32 v39, v74
	v_pk_mul_f32 v[88:89], v[22:23], v[22:23]
	v_pk_mul_f32 v[84:85], v[24:25], v[24:25]
	v_mov_b32_e32 v76, v59
	v_mov_b32_e32 v77, v75
	v_pk_fma_f32 v[28:29], v[38:39], v[38:39], v[28:29]
	v_mov_b32_e32 v38, v84
	v_pk_fma_f32 v[28:29], v[76:77], v[76:77], v[28:29]
	v_mov_b32_e32 v39, v88
	v_pk_add_f32 v[38:39], v[38:39], v[28:29]
	v_lshlrev_b32_e32 v28, 16, v87
	v_and_b32_e32 v29, 0xffff0000, v87
	v_pk_mul_f32 v[90:91], v[26:27], v[26:27]
	v_pk_mul_f32 v[76:77], v[28:29], v[28:29]
	v_mov_b32_e32 v88, v85
	v_pk_add_f32 v[38:39], v[88:89], v[38:39]
	v_mov_b32_e32 v84, v76
	v_mov_b32_e32 v85, v90
	v_pk_add_f32 v[38:39], v[84:85], v[38:39]
	v_mov_b32_e32 v90, v77
	v_pk_add_f32 v[38:39], v[90:91], v[38:39]
	ds_bpermute_b32 v77, v78, v39
	ds_bpermute_b32 v76, v78, v38
	v_mov_b64_e32 v[88:89], s[68:69]
	v_lshlrev_b32_e32 v68, 16, v36
	v_and_b32_e32 v69, 0xffff0000, v36
	v_lshlrev_b32_e32 v36, 16, v63
	s_waitcnt lgkmcnt(0)
	v_pk_add_f32 v[38:39], v[38:39], v[76:77]
	ds_bpermute_b32 v77, v79, v39
	ds_bpermute_b32 v76, v79, v38
	v_lshlrev_b32_e32 v66, 16, v37
	v_and_b32_e32 v67, 0xffff0000, v37
	v_and_b32_e32 v37, 0xffff0000, v63
	v_mov_b32_e32 v62, v36
	s_waitcnt lgkmcnt(0)
	v_pk_add_f32 v[38:39], v[38:39], v[76:77]
	ds_bpermute_b32 v77, v80, v39
	ds_bpermute_b32 v76, v80, v38
	v_mov_b32_e32 v63, v70
	v_pk_fma_f32 v[60:61], v[62:63], v[62:63], v[60:61]
	v_mov_b32_e32 v62, v32
	v_mov_b32_e32 v63, v68
	s_waitcnt lgkmcnt(0)
	v_pk_add_f32 v[38:39], v[38:39], v[76:77]
	ds_bpermute_b32 v77, v81, v39
	ds_bpermute_b32 v76, v81, v38
	s_waitcnt lgkmcnt(0)
	v_pk_add_f32 v[38:39], v[38:39], v[76:77]
	ds_bpermute_b32 v77, v82, v39
	ds_bpermute_b32 v76, v82, v38
	s_waitcnt lgkmcnt(0)
	v_pk_add_f32 v[38:39], v[38:39], v[76:77]
	ds_bpermute_b32 v77, v83, v39
	ds_bpermute_b32 v76, v83, v38
	s_waitcnt lgkmcnt(0)
	v_pk_add_f32 v[38:39], v[38:39], v[76:77]
	s_nop 0
	v_pk_fma_f32 v[76:77], v[38:39], s[74:75], v[88:89] op_sel_hi:[1,0,0]
	s_nop 0
	v_mul_f32_e32 v38, 0x4b800000, v77
	v_cmp_gt_f32_e64 s[40:41], s19, v77
	v_cmp_gt_f32_e32 vcc, s19, v76
	s_nop 0
	v_cndmask_b32_e64 v38, v77, v38, s[40:41]
	v_rsq_f32_e32 v38, v38
	s_nop 0
	v_mul_f32_e32 v39, 0x45800000, v38
	v_cndmask_b32_e64 v38, v38, v39, s[40:41]
	v_pk_mul_f32 v[40:41], v[38:39], v[40:41] op_sel_hi:[0,1]
	v_pk_mul_f32 v[46:47], v[38:39], v[46:47] op_sel_hi:[0,1]
	s_waitcnt vmcnt(0)
	v_mov_b32_e32 v0, v104
	v_mov_b32_e32 v1, v105
	v_mov_b32_e32 v2, v106
	v_mov_b32_e32 v3, v107
	v_mov_b32_e32 v4, v100
	v_mov_b32_e32 v5, v101
	v_mov_b32_e32 v6, v102
	v_mov_b32_e32 v7, v103
	v_pk_mul_f32 v[86:87], v[6:7], v[40:41]
	v_add_co_u32_e64 v40, s[40:41], s1, v18
	v_pk_mul_f32 v[44:45], v[38:39], v[44:45] op_sel_hi:[0,1]
	v_pk_mul_f32 v[42:43], v[38:39], v[42:43] op_sel_hi:[0,1]
	v_pk_mul_f32 v[84:85], v[4:5], v[46:47]
	v_addc_co_u32_e64 v41, s[40:41], -1, v19, s[40:41]
	v_pk_mul_f32 v[44:45], v[0:1], v[44:45]
	v_pk_mul_f32 v[46:47], v[2:3], v[42:43]
	global_store_dwordx4 v[40:41], v[44:47], off offset:-2048
	global_store_dwordx4 v[40:41], v[84:87], off offset:-2064
	s_movk_i32 s1, 0xe000
	v_pk_mul_f32 v[44:45], v[38:39], v[64:65] op_sel_hi:[0,1]
	v_pk_mul_f32 v[46:47], v[38:39], v[74:75] op_sel_hi:[0,1]
	v_mul_f32_e32 v39, 0x4b800000, v76
	v_cndmask_b32_e32 v39, v76, v39, vcc
	v_rsq_f32_e32 v39, v39
	v_mov_b32_e32 v86, v37
	v_mov_b32_e32 v87, v71
	v_pk_fma_f32 v[60:61], v[86:87], v[86:87], v[60:61]
	v_mul_f32_e32 v42, 0x45800000, v39
	v_cndmask_b32_e32 v42, v39, v42, vcc
	v_pk_mul_f32 v[48:49], v[42:43], v[48:49] op_sel_hi:[0,1]
	v_pk_mul_f32 v[74:75], v[4:5], v[48:49]
	v_pk_mul_f32 v[48:49], v[42:43], v[56:57] op_sel_hi:[0,1]
	v_pk_mul_f32 v[76:77], v[6:7], v[48:49]
	v_add_co_u32_e32 v48, vcc, s1, v18
	v_pk_mul_f32 v[52:53], v[42:43], v[52:53] op_sel_hi:[0,1]
	s_nop 0
	v_addc_co_u32_e32 v49, vcc, -1, v19, vcc
	v_pk_mul_f32 v[50:51], v[42:43], v[50:51] op_sel_hi:[0,1]
	v_mov_b32_e32 v86, v33
	v_mov_b32_e32 v87, v69
	v_pk_fma_f32 v[60:61], v[62:63], v[62:63], v[60:61]
	global_store_dwordx4 v[48:49], v[74:77], off offset:-2064
	v_pk_fma_f32 v[60:61], v[86:87], v[86:87], v[60:61]
	v_mov_b32_e32 v62, v30
	v_pk_mul_f32 v[74:75], v[0:1], v[52:53]
	v_pk_mul_f32 v[76:77], v[2:3], v[50:51]
	v_mov_b32_e32 v63, v66
	global_store_dwordx4 v[48:49], v[74:77], off offset:-2048
	v_lshlrev_b32_e32 v52, 16, v8
	v_mov_b32_e32 v86, v31
	v_lshlrev_b32_e32 v74, 16, v12
	v_mov_b32_e32 v87, v67
	v_pk_fma_f32 v[60:61], v[62:63], v[62:63], v[60:61]
	v_and_b32_e32 v75, 0xffff0000, v12
	v_and_b32_e32 v53, 0xffff0000, v8
	v_pk_fma_f32 v[60:61], v[86:87], v[86:87], v[60:61]
	v_mov_b32_e32 v62, v52
	v_mov_b32_e32 v63, v74
	v_lshlrev_b32_e32 v76, 16, v13
	v_lshlrev_b32_e32 v50, 16, v14
	v_and_b32_e32 v51, 0xffff0000, v14
	v_lshlrev_b32_e32 v14, 16, v9
	v_mov_b32_e32 v86, v53
	v_mov_b32_e32 v87, v75
	v_pk_fma_f32 v[60:61], v[62:63], v[62:63], v[60:61]
	v_pk_mul_f32 v[56:57], v[42:43], v[54:55] op_sel_hi:[0,1]
	v_and_b32_e32 v77, 0xffff0000, v13
	v_lshlrev_b32_e32 v54, 16, v15
	v_and_b32_e32 v55, 0xffff0000, v15
	v_and_b32_e32 v15, 0xffff0000, v9
	v_lshlrev_b32_e32 v12, 16, v10
	v_and_b32_e32 v13, 0xffff0000, v10
	v_pk_fma_f32 v[60:61], v[86:87], v[86:87], v[60:61]
	v_mov_b32_e32 v62, v14
	v_mov_b32_e32 v63, v76
	v_pk_mul_f32 v[64:65], v[50:51], v[50:51]
	v_pk_mul_f32 v[8:9], v[12:13], v[12:13]
	v_mov_b32_e32 v86, v15
	v_mov_b32_e32 v87, v77
	v_pk_fma_f32 v[60:61], v[62:63], v[62:63], v[60:61]
	v_mov_b32_e32 v62, v8
	v_pk_fma_f32 v[60:61], v[86:87], v[86:87], v[60:61]
	v_mov_b32_e32 v63, v64
	v_pk_add_f32 v[62:63], v[62:63], v[60:61]
	v_lshlrev_b32_e32 v60, 16, v11
	v_and_b32_e32 v61, 0xffff0000, v11
	v_pk_mul_f32 v[84:85], v[54:55], v[54:55]
	v_pk_mul_f32 v[10:11], v[60:61], v[60:61]
	v_mov_b32_e32 v64, v9
	v_pk_add_f32 v[8:9], v[64:65], v[62:63]
	v_mov_b32_e32 v62, v10
	v_mov_b32_e32 v63, v84
	v_pk_add_f32 v[8:9], v[62:63], v[8:9]
	v_mov_b32_e32 v84, v11
	v_pk_add_f32 v[8:9], v[84:85], v[8:9]
	ds_bpermute_b32 v11, v78, v9
	ds_bpermute_b32 v10, v78, v8
	v_pk_mul_f32 v[58:59], v[42:43], v[58:59] op_sel_hi:[0,1]
	s_movk_i32 s1, 0xf000
	s_waitcnt lgkmcnt(0)
	v_pk_add_f32 v[8:9], v[8:9], v[10:11]
	ds_bpermute_b32 v11, v79, v9
	ds_bpermute_b32 v10, v79, v8
	s_waitcnt lgkmcnt(0)
	v_pk_add_f32 v[8:9], v[8:9], v[10:11]
	ds_bpermute_b32 v11, v80, v9
	ds_bpermute_b32 v10, v80, v8
	s_waitcnt lgkmcnt(0)
	v_pk_add_f32 v[8:9], v[8:9], v[10:11]
	ds_bpermute_b32 v11, v81, v9
	ds_bpermute_b32 v10, v81, v8
	s_waitcnt lgkmcnt(0)
	v_pk_add_f32 v[8:9], v[8:9], v[10:11]
	ds_bpermute_b32 v11, v82, v9
	ds_bpermute_b32 v10, v82, v8
	s_waitcnt lgkmcnt(0)
	v_pk_add_f32 v[8:9], v[8:9], v[10:11]
	ds_bpermute_b32 v11, v83, v9
	ds_bpermute_b32 v10, v83, v8
	s_waitcnt lgkmcnt(0)
	v_pk_add_f32 v[8:9], v[8:9], v[10:11]
	s_nop 0
	v_pk_fma_f32 v[64:65], v[8:9], s[74:75], v[88:89] op_sel_hi:[1,0,0]
	s_nop 0
	v_mul_f32_e32 v8, 0x4b800000, v65
	v_cmp_gt_f32_e32 vcc, s19, v64
	v_cmp_gt_f32_e64 s[40:41], s19, v65
	v_mul_f32_e32 v39, 0x4b800000, v64
	v_cndmask_b32_e32 v39, v64, v39, vcc
	v_cndmask_b32_e64 v8, v65, v8, s[40:41]
	v_rsq_f32_e32 v8, v8
	v_rsq_f32_e32 v39, v39
	v_mul_f32_e32 v9, 0x45800000, v8
	v_mul_f32_e32 v43, 0x45800000, v39
	v_cndmask_b32_e64 v62, v8, v9, s[40:41]
	v_cndmask_b32_e32 v64, v39, v43, vcc
	v_pk_mul_f32 v[8:9], v[62:63], v[72:73] op_sel_hi:[0,1]
	v_pk_mul_f32 v[34:35], v[64:65], v[34:35] op_sel_hi:[0,1]
	v_pk_mul_f32 v[8:9], v[4:5], v[8:9]
	v_pk_mul_f32 v[10:11], v[62:63], v[70:71] op_sel_hi:[0,1]
	v_add_co_u32_e64 v70, s[40:41], s1, v18
	v_pk_mul_f32 v[4:5], v[4:5], v[34:35]
	v_pk_mul_f32 v[34:35], v[64:65], v[36:37] op_sel_hi:[0,1]
	v_pk_mul_f32 v[10:11], v[6:7], v[10:11]
	v_addc_co_u32_e64 v71, s[40:41], -1, v19, s[40:41]
	v_pk_mul_f32 v[6:7], v[6:7], v[34:35]
	global_store_dwordx4 v[70:71], v[8:11], off offset:-2064
	global_store_dwordx4 v[18:19], v[4:7], off offset:-2064
	v_pk_mul_f32 v[26:27], v[38:39], v[26:27] op_sel_hi:[0,1]
	v_pk_mul_f32 v[8:9], v[62:63], v[68:69] op_sel_hi:[0,1]
	v_pk_mul_f32 v[4:5], v[64:65], v[32:33] op_sel_hi:[0,1]
	v_pk_mul_f32 v[8:9], v[0:1], v[8:9]
	v_pk_mul_f32 v[10:11], v[62:63], v[66:67] op_sel_hi:[0,1]
	v_pk_mul_f32 v[0:1], v[0:1], v[4:5]
	v_pk_mul_f32 v[4:5], v[64:65], v[30:31] op_sel_hi:[0,1]
	v_pk_mul_f32 v[10:11], v[2:3], v[10:11]
	v_pk_mul_f32 v[2:3], v[2:3], v[4:5]
	global_store_dwordx4 v[70:71], v[8:11], off offset:-2048
	global_store_dwordx4 v[18:19], v[0:3], off offset:-2048
	s_nop 1
	v_mov_b32_e32 v0, v112
	v_mov_b32_e32 v1, v113
	v_mov_b32_e32 v2, v114
	v_mov_b32_e32 v3, v115
	v_mov_b32_e32 v4, v108
	v_mov_b32_e32 v5, v109
	v_mov_b32_e32 v6, v110
	v_mov_b32_e32 v7, v111
	v_pk_mul_f32 v[8:9], v[62:63], v[74:75] op_sel_hi:[0,1]
	v_pk_mul_f32 v[10:11], v[62:63], v[76:77] op_sel_hi:[0,1]
	v_pk_mul_f32 v[22:23], v[38:39], v[22:23] op_sel_hi:[0,1]
	v_pk_mul_f32 v[8:9], v[8:9], v[4:5]
	v_pk_mul_f32 v[10:11], v[10:11], v[6:7]
	global_store_dwordx4 v[70:71], v[8:11], off offset:-16
	v_pk_mul_f32 v[30:31], v[44:45], v[4:5]
	v_pk_mul_f32 v[32:33], v[46:47], v[6:7]
	v_pk_mul_f32 v[10:11], v[62:63], v[54:55] op_sel_hi:[0,1]
	v_pk_mul_f32 v[8:9], v[62:63], v[50:51] op_sel_hi:[0,1]
	v_pk_mul_f32 v[8:9], v[8:9], v[0:1]
	v_pk_mul_f32 v[10:11], v[10:11], v[2:3]
	global_store_dwordx4 v[40:41], v[30:33], off offset:-16
	global_store_dwordx4 v[18:19], v[8:11], off offset:-4096
	s_nop 0
	v_pk_mul_f32 v[30:31], v[22:23], v[0:1]
	v_pk_mul_f32 v[32:33], v[26:27], v[2:3]
	v_pk_mul_f32 v[8:9], v[64:65], v[52:53] op_sel_hi:[0,1]
	global_store_dwordx4 v[48:49], v[30:33], off offset:-4096
	v_pk_mul_f32 v[26:27], v[42:43], v[28:29] op_sel_hi:[0,1]
	v_pk_mul_f32 v[22:23], v[42:43], v[24:25] op_sel_hi:[0,1]
	v_pk_mul_f32 v[30:31], v[56:57], v[4:5]
	v_pk_mul_f32 v[4:5], v[8:9], v[4:5]
	v_pk_mul_f32 v[8:9], v[64:65], v[14:15] op_sel_hi:[0,1]
	v_pk_mul_f32 v[32:33], v[58:59], v[6:7]
	v_pk_mul_f32 v[6:7], v[8:9], v[6:7]
	global_store_dwordx4 v[18:19], v[4:7], off offset:-16
	v_pk_mul_f32 v[22:23], v[22:23], v[0:1]
	v_pk_mul_f32 v[24:25], v[26:27], v[2:3]
	v_pk_mul_f32 v[4:5], v[64:65], v[60:61] op_sel_hi:[0,1]
	v_pk_mul_f32 v[6:7], v[64:65], v[12:13] op_sel_hi:[0,1]
	v_pk_mul_f32 v[0:1], v[6:7], v[0:1]
	v_pk_mul_f32 v[2:3], v[4:5], v[2:3]
	global_store_dwordx4 v[18:19], v[0:3], off
	v_lshl_add_u64 v[18:19], v[18:19], 0, s[66:67]
	global_store_dwordx4 v[48:49], v[30:33], off offset:-16
	global_store_dwordx4 v[48:49], v[22:25], off
	s_cbranch_scc0 .LBB0_300

.LBB0_307:
	v_readlane_b32 s0, v245, 20
	v_readlane_b32 s1, v245, 21
	s_add_u32 s0, s0, 0x3000000
	s_addc_u32 s1, s1, 0
	v_writelane_b32 v245, s0, 29
	s_cmp_lt_i32 s2, 0
	s_nop 0
	v_writelane_b32 v245, s1, 30
	s_cbranch_scc1 .LBB0_311
	s_cmpk_gt_i32 s20, 0xfff
	s_cbranch_scc1 .LBB0_311
	v_sub_co_u32_e64 v0, s[0:1], s2, 1
	s_nop 0
	v_readfirstlane_b32 s2, v0
	v_and_b32_e32 v0, 64, v199
	v_add_u32_e32 v0, 64, v0
	v_xor_b32_e32 v1, 1, v199
	v_cmp_lt_i32_e32 vcc, v1, v0
	v_readlane_b32 s48, v247, 2
	v_readlane_b32 s49, v247, 3
	v_cndmask_b32_e32 v1, v199, v1, vcc
	v_lshlrev_b32_e32 v82, 2, v1
	v_xor_b32_e32 v1, 2, v199
	v_cmp_lt_i32_e32 vcc, v1, v0
	s_mov_b32 s3, s96
	v_readlane_b32 s50, v247, 4
	v_cndmask_b32_e32 v1, v199, v1, vcc
	v_lshlrev_b32_e32 v83, 2, v1
	v_xor_b32_e32 v1, 4, v199
	v_cmp_lt_i32_e32 vcc, v1, v0
	v_readlane_b32 s51, v247, 5
	v_readlane_b32 s52, v247, 6
	v_cndmask_b32_e32 v1, v199, v1, vcc
	v_readlane_b32 s53, v247, 7
	s_mov_b64 s[8:9], s[48:49]
	v_lshlrev_b32_e32 v84, 2, v1
	v_xor_b32_e32 v1, 8, v199
	s_lshl_b64 s[2:3], s[2:3], 26
	s_mov_b64 s[10:11], s[50:51]
	v_cmp_lt_i32_e32 vcc, v1, v0
	s_add_u32 s2, s10, s2
	s_addc_u32 s3, s11, s3
	v_cndmask_b32_e32 v1, v199, v1, vcc
	v_lshlrev_b32_e32 v85, 2, v1
	v_xor_b32_e32 v1, 16, v199
	s_and_b64 s[0:1], s[0:1], exec
	v_cmp_lt_i32_e32 vcc, v1, v0
	s_cselect_b32 s6, s9, s3
	s_cselect_b32 s7, s8, s2
	s_lshl_b32 s0, s20, 2
	v_cndmask_b32_e32 v1, v199, v1, vcc
	v_lshlrev_b32_e32 v86, 2, v1
	v_xor_b32_e32 v1, 32, v199
	s_ashr_i32 s1, s0, 31
	v_cmp_lt_i32_e32 vcc, v1, v0
	s_lshl_b64 s[2:3], s[0:1], 11
	v_readlane_b32 s8, v245, 29
	v_cndmask_b32_e32 v0, v199, v1, vcc
	v_readlane_b32 s9, v245, 30
	s_add_u32 s2, s8, s2
	v_lshlrev_b32_e32 v87, 2, v0
	v_lshlrev_b32_e32 v0, 3, v201
	v_mov_b32_e32 v1, v155
	s_addc_u32 s3, s9, s3
	v_lshl_add_u64 v[70:71], s[2:3], 0, v[0:1]
	s_lshl_b64 s[2:3], s[0:1], 12
	s_add_u32 s2, s7, s2
	s_mov_b64 s[12:13], s[52:53]
	v_lshlrev_b32_e32 v154, 4, v201
	s_addc_u32 s3, s6, s3
	v_lshl_add_u64 v[68:69], s[12:13], 0, v[154:155]
	v_lshl_add_u64 v[72:73], s[2:3], 0, v[154:155]
	v_readlane_b32 s54, v247, 8
	v_readlane_b32 s55, v247, 9
	v_readlane_b32 s56, v247, 10
	v_readlane_b32 s57, v247, 11
	v_readlane_b32 s58, v247, 12
	v_readlane_b32 s59, v247, 13
	v_readlane_b32 s60, v247, 14
	v_readlane_b32 s61, v247, 15
	v_readlane_b32 s62, v247, 16
	v_readlane_b32 s63, v247, 17
	global_load_dwordx4 v[100:103], v[68:69], off
	global_load_dwordx4 v[104:107], v[68:69], off offset:1024
	global_load_dwordx4 v[108:111], v[68:69], off offset:2048
	global_load_dwordx4 v[112:115], v[68:69], off offset:3072
.LBB0_310:
	global_load_dwordx4 v[60:63], v[72:73], off
	global_load_dwordx4 v[44:47], v[72:73], off offset:1024
	global_load_dwordx4 v[28:31], v[72:73], off offset:2048
	global_load_dwordx4 v[0:3], v[72:73], off offset:3072
	v_add_co_u32_e32 v4, vcc, 0x1000, v72
	s_add_i32 s0, s0, s30
	s_nop 0
	v_addc_co_u32_e32 v5, vcc, 0, v73, vcc
	global_load_dwordx4 v[64:67], v[4:5], off
	global_load_dwordx4 v[40:43], v[4:5], off offset:1024
	global_load_dwordx4 v[24:27], v[4:5], off offset:2048
	s_nop 0
	global_load_dwordx4 v[4:7], v[4:5], off offset:3072
	v_add_co_u32_e32 v8, vcc, s69, v72
	s_cmpk_lt_i32 s0, 0x4000
	s_nop 0
	v_addc_co_u32_e32 v9, vcc, 0, v73, vcc
	v_add_co_u32_e32 v10, vcc, s64, v72
	s_waitcnt vmcnt(7)
	v_pk_mul_f32 v[52:53], v[62:63], v[62:63]
	v_addc_co_u32_e32 v11, vcc, 0, v73, vcc
	global_load_dwordx4 v[56:59], v[10:11], off offset:-4096
	global_load_dwordx4 v[36:39], v[8:9], off offset:1024
	global_load_dwordx4 v[20:23], v[8:9], off offset:2048
	global_load_dwordx4 v[12:15], v[8:9], off offset:3072
	global_load_dwordx4 v[48:51], v[10:11], off
	global_load_dwordx4 v[32:35], v[10:11], off offset:1024
	global_load_dwordx4 v[16:19], v[10:11], off offset:2048
	s_nop 0
	global_load_dwordx4 v[8:11], v[10:11], off offset:3072
	v_pk_mul_f32 v[54:55], v[60:61], v[60:61]
	v_lshl_add_u64 v[72:73], v[72:73], 0, s[66:67]
	v_pk_mov_b32 v[74:75], v[54:55], v[52:53] op_sel:[1,0]
	v_mov_b32_e32 v55, v53
	v_pk_add_f32 v[52:53], v[74:75], v[54:55]
	s_waitcnt vmcnt(14)
	v_pk_mul_f32 v[54:55], v[46:47], v[46:47]
	v_pk_mul_f32 v[74:75], v[44:45], v[44:45]
	v_pk_add_f32 v[52:53], v[52:53], v[52:53] op_sel:[0,1] op_sel_hi:[1,0]
	v_pk_mov_b32 v[76:77], v[74:75], v[54:55] op_sel:[1,0]
	v_mov_b32_e32 v75, v55
	v_pk_add_f32 v[54:55], v[76:77], v[74:75]
	s_waitcnt vmcnt(12)
	v_mul_f32_e32 v74, v0, v0
	v_mul_f32_e32 v75, v1, v1
	v_pk_add_f32 v[54:55], v[54:55], v[54:55] op_sel:[0,1] op_sel_hi:[1,0]
	v_mov_b32_e32 v53, v74
	v_mov_b32_e32 v55, v75
	v_pk_add_f32 v[52:53], v[52:53], v[54:55]
	v_mul_f32_e32 v54, v29, v29
	v_mul_f32_e32 v74, v31, v31
	v_mul_f32_e32 v76, v2, v2
	v_mul_f32_e32 v77, v3, v3
	v_pk_fma_f32 v[54:55], v[28:29], v[28:29], v[54:55] op_sel_hi:[1,1,0]
	v_pk_fma_f32 v[74:75], v[30:31], v[30:31], v[74:75] op_sel_hi:[1,1,0]
	v_mov_b32_e32 v55, v76
	v_mov_b32_e32 v75, v77
	v_pk_add_f32 v[54:55], v[54:55], v[74:75]
	s_nop 0
	v_pk_add_f32 v[74:75], v[52:53], v[54:55]
	s_waitcnt vmcnt(11)
	v_pk_mul_f32 v[52:53], v[66:67], v[66:67]
	v_pk_mul_f32 v[54:55], v[64:65], v[64:65]
	s_nop 0
	v_pk_mov_b32 v[76:77], v[54:55], v[52:53] op_sel:[1,0]
	v_mov_b32_e32 v55, v53
	v_pk_add_f32 v[52:53], v[76:77], v[54:55]
	s_waitcnt vmcnt(10)
	v_pk_mul_f32 v[54:55], v[42:43], v[42:43]
	v_pk_mul_f32 v[76:77], v[40:41], v[40:41]
	v_pk_add_f32 v[52:53], v[52:53], v[52:53] op_sel:[0,1] op_sel_hi:[1,0]
	v_pk_mov_b32 v[78:79], v[76:77], v[54:55] op_sel:[1,0]
	v_mov_b32_e32 v77, v55
	v_pk_add_f32 v[54:55], v[78:79], v[76:77]
	s_waitcnt vmcnt(8)
	v_mul_f32_e32 v76, v4, v4
	v_mul_f32_e32 v77, v5, v5
	v_pk_add_f32 v[54:55], v[54:55], v[54:55] op_sel:[0,1] op_sel_hi:[1,0]
	v_mov_b32_e32 v53, v76
	v_mov_b32_e32 v55, v77
	v_pk_add_f32 v[52:53], v[52:53], v[54:55]
	v_mul_f32_e32 v54, v25, v25
	v_mul_f32_e32 v76, v27, v27
	v_mul_f32_e32 v78, v6, v6
	v_mul_f32_e32 v79, v7, v7
	v_pk_fma_f32 v[54:55], v[24:25], v[24:25], v[54:55] op_sel_hi:[1,1,0]
	v_pk_fma_f32 v[76:77], v[26:27], v[26:27], v[76:77] op_sel_hi:[1,1,0]
	v_mov_b32_e32 v55, v78
	v_mov_b32_e32 v77, v79
	v_pk_add_f32 v[54:55], v[54:55], v[76:77]
	s_nop 0
	v_pk_add_f32 v[80:81], v[52:53], v[54:55]
	s_waitcnt vmcnt(7)
	v_pk_mul_f32 v[52:53], v[58:59], v[58:59]
	v_pk_mul_f32 v[54:55], v[56:57], v[56:57]
	s_nop 0
	v_pk_mov_b32 v[76:77], v[54:55], v[52:53] op_sel:[1,0]
	v_mov_b32_e32 v55, v53
	v_pk_add_f32 v[52:53], v[76:77], v[54:55]
	s_waitcnt vmcnt(6)
	v_pk_mul_f32 v[54:55], v[38:39], v[38:39]
	v_pk_mul_f32 v[76:77], v[36:37], v[36:37]
	v_pk_add_f32 v[52:53], v[52:53], v[52:53] op_sel:[0,1] op_sel_hi:[1,0]
	v_pk_mov_b32 v[78:79], v[76:77], v[54:55] op_sel:[1,0]
	v_mov_b32_e32 v77, v55
	v_pk_add_f32 v[54:55], v[78:79], v[76:77]
	s_waitcnt vmcnt(4)
	v_mul_f32_e32 v76, v12, v12
	v_mul_f32_e32 v77, v13, v13
	v_pk_add_f32 v[54:55], v[54:55], v[54:55] op_sel:[0,1] op_sel_hi:[1,0]
	v_mov_b32_e32 v53, v76
	v_mov_b32_e32 v55, v77
	v_pk_add_f32 v[52:53], v[52:53], v[54:55]
	v_mul_f32_e32 v54, v21, v21
	v_mul_f32_e32 v76, v23, v23
	v_mul_f32_e32 v78, v14, v14
	v_mul_f32_e32 v79, v15, v15
	v_pk_fma_f32 v[54:55], v[20:21], v[20:21], v[54:55] op_sel_hi:[1,1,0]
	v_pk_fma_f32 v[76:77], v[22:23], v[22:23], v[76:77] op_sel_hi:[1,1,0]
	v_mov_b32_e32 v55, v78
	v_mov_b32_e32 v77, v79
	v_pk_add_f32 v[54:55], v[54:55], v[76:77]
	s_nop 0
	v_pk_add_f32 v[76:77], v[52:53], v[54:55]
	s_waitcnt vmcnt(3)
	v_pk_mul_f32 v[52:53], v[50:51], v[50:51]
	v_pk_mul_f32 v[54:55], v[48:49], v[48:49]
	s_nop 0
	v_pk_mov_b32 v[78:79], v[54:55], v[52:53] op_sel:[1,0]
	v_mov_b32_e32 v55, v53
	v_pk_add_f32 v[52:53], v[78:79], v[54:55]
	s_waitcnt vmcnt(2)
	v_pk_mul_f32 v[54:55], v[34:35], v[34:35]
	v_pk_mul_f32 v[78:79], v[32:33], v[32:33]
	v_pk_add_f32 v[52:53], v[52:53], v[52:53] op_sel:[0,1] op_sel_hi:[1,0]
	v_pk_mov_b32 v[88:89], v[78:79], v[54:55] op_sel:[1,0]
	v_mov_b32_e32 v79, v55
	v_pk_add_f32 v[54:55], v[88:89], v[78:79]
	s_waitcnt vmcnt(0)
	v_mul_f32_e32 v78, v8, v8
	v_mul_f32_e32 v79, v9, v9
	v_pk_add_f32 v[54:55], v[54:55], v[54:55] op_sel:[0,1] op_sel_hi:[1,0]
	v_mov_b32_e32 v53, v78
	v_mov_b32_e32 v55, v79
	v_pk_add_f32 v[52:53], v[52:53], v[54:55]
	v_mul_f32_e32 v54, v17, v17
	v_mul_f32_e32 v78, v19, v19
	v_mul_f32_e32 v88, v10, v10
	v_mul_f32_e32 v89, v11, v11
	v_pk_fma_f32 v[54:55], v[16:17], v[16:17], v[54:55] op_sel_hi:[1,1,0]
	v_pk_fma_f32 v[78:79], v[18:19], v[18:19], v[78:79] op_sel_hi:[1,1,0]
	v_mov_b32_e32 v55, v88
	v_mov_b32_e32 v79, v89
	v_pk_add_f32 v[54:55], v[54:55], v[78:79]
	v_mov_b32_e32 v88, v80
	v_pk_add_f32 v[78:79], v[52:53], v[54:55]
	v_mov_b32_e32 v52, v100
	v_mov_b32_e32 v53, v101
	v_mov_b32_e32 v54, v102
	v_mov_b32_e32 v55, v103
	v_mov_b32_e32 v89, v74
	v_mov_b32_e32 v74, v81
	v_pk_add_f32 v[74:75], v[88:89], v[74:75]
	ds_bpermute_b32 v81, v82, v75
	ds_bpermute_b32 v80, v82, v74
	s_waitcnt lgkmcnt(0)
	v_pk_add_f32 v[74:75], v[74:75], v[80:81]
	ds_bpermute_b32 v81, v83, v75
	ds_bpermute_b32 v80, v83, v74
	s_waitcnt lgkmcnt(0)
	v_pk_add_f32 v[74:75], v[74:75], v[80:81]
	ds_bpermute_b32 v81, v84, v75
	ds_bpermute_b32 v80, v84, v74
	s_waitcnt lgkmcnt(0)
	v_pk_add_f32 v[74:75], v[74:75], v[80:81]
	ds_bpermute_b32 v81, v85, v75
	ds_bpermute_b32 v80, v85, v74
	s_waitcnt lgkmcnt(0)
	v_pk_add_f32 v[74:75], v[74:75], v[80:81]
	ds_bpermute_b32 v81, v86, v75
	ds_bpermute_b32 v80, v86, v74
	s_waitcnt lgkmcnt(0)
	v_pk_add_f32 v[74:75], v[74:75], v[80:81]
	ds_bpermute_b32 v81, v87, v75
	ds_bpermute_b32 v80, v87, v74
	s_waitcnt lgkmcnt(0)
	v_pk_add_f32 v[74:75], v[74:75], v[80:81]
	v_mov_b64_e32 v[80:81], s[68:69]
	v_pk_fma_f32 v[88:89], v[74:75], s[74:75], v[80:81] op_sel_hi:[1,0,0]
	s_nop 0
	v_mul_f32_e32 v74, 0x4b800000, v89
	v_cmp_gt_f32_e64 s[38:39], s19, v89
	v_cmp_gt_f32_e32 vcc, s19, v88
	s_nop 0
	v_cndmask_b32_e64 v74, v89, v74, s[38:39]
	v_rsq_f32_e32 v74, v74
	s_nop 0
	v_mul_f32_e32 v75, 0x45800000, v74
	v_cndmask_b32_e64 v74, v74, v75, s[38:39]
	v_pk_mul_f32 v[60:61], v[60:61], v[74:75] op_sel_hi:[1,0]
	v_pk_mul_f32 v[62:63], v[62:63], v[74:75] op_sel_hi:[1,0]
	v_pk_mul_f32 v[44:45], v[44:45], v[74:75] op_sel_hi:[1,0]
	v_pk_mul_f32 v[46:47], v[46:47], v[74:75] op_sel_hi:[1,0]
	v_pk_mul_f32 v[28:29], v[28:29], v[74:75] op_sel_hi:[1,0]
	v_pk_mul_f32 v[30:31], v[30:31], v[74:75] op_sel_hi:[1,0]
	v_pk_mul_f32 v[0:1], v[0:1], v[74:75] op_sel_hi:[1,0]
	v_pk_mul_f32 v[2:3], v[2:3], v[74:75] op_sel_hi:[1,0]
	v_pk_mul_f32 v[60:61], v[52:53], v[60:61]
	v_pk_mul_f32 v[62:63], v[54:55], v[62:63]
	v_cvt_pk_bf16_f32 v60, v60, v61
	v_cvt_pk_bf16_f32 v61, v62, v63
	global_store_dwordx2 v[70:71], v[60:61], off
	v_mul_f32_e32 v60, 0x4b800000, v88
	v_cndmask_b32_e32 v60, v88, v60, vcc
	v_rsq_f32_e32 v60, v60
	s_nop 0
	v_mul_f32_e32 v61, 0x45800000, v60
	v_cndmask_b32_e32 v60, v60, v61, vcc
	v_pk_mul_f32 v[62:63], v[64:65], v[60:61] op_sel_hi:[1,0]
	v_pk_mul_f32 v[64:65], v[66:67], v[60:61] op_sel_hi:[1,0]
	v_pk_mul_f32 v[62:63], v[52:53], v[62:63]
	v_pk_mul_f32 v[64:65], v[54:55], v[64:65]
	v_cvt_pk_bf16_f32 v62, v62, v63
	v_cvt_pk_bf16_f32 v63, v64, v65
	global_store_dwordx2 v[70:71], v[62:63], off offset:2048
	v_mov_b32_e32 v62, v78
	v_mov_b32_e32 v63, v76
	v_mov_b32_e32 v76, v79
	v_pk_add_f32 v[62:63], v[62:63], v[76:77]
	ds_bpermute_b32 v65, v82, v63
	ds_bpermute_b32 v64, v82, v62
	s_waitcnt lgkmcnt(0)
	v_pk_add_f32 v[62:63], v[62:63], v[64:65]
	ds_bpermute_b32 v65, v83, v63
	ds_bpermute_b32 v64, v83, v62
	s_waitcnt lgkmcnt(0)
	v_pk_add_f32 v[62:63], v[62:63], v[64:65]
	ds_bpermute_b32 v65, v84, v63
	ds_bpermute_b32 v64, v84, v62
	s_waitcnt lgkmcnt(0)
	v_pk_add_f32 v[62:63], v[62:63], v[64:65]
	ds_bpermute_b32 v65, v85, v63
	ds_bpermute_b32 v64, v85, v62
	s_waitcnt lgkmcnt(0)
	v_pk_add_f32 v[62:63], v[62:63], v[64:65]
	ds_bpermute_b32 v65, v86, v63
	ds_bpermute_b32 v64, v86, v62
	s_waitcnt lgkmcnt(0)
	v_pk_add_f32 v[62:63], v[62:63], v[64:65]
	ds_bpermute_b32 v65, v87, v63
	ds_bpermute_b32 v64, v87, v62
	s_waitcnt lgkmcnt(0)
	v_pk_add_f32 v[62:63], v[62:63], v[64:65]
	s_nop 0
	v_pk_fma_f32 v[64:65], v[62:63], s[74:75], v[80:81] op_sel_hi:[1,0,0]
	s_nop 0
	v_mul_f32_e32 v61, 0x4b800000, v65
	v_cmp_gt_f32_e64 s[38:39], s19, v65
	v_cmp_gt_f32_e32 vcc, s19, v64
	s_nop 0
	v_cndmask_b32_e64 v61, v65, v61, s[38:39]
	v_rsq_f32_e32 v61, v61
	s_nop 0
	v_mul_f32_e32 v62, 0x45800000, v61
	v_cndmask_b32_e64 v62, v61, v62, s[38:39]
	v_pk_mul_f32 v[56:57], v[56:57], v[62:63] op_sel_hi:[1,0]
	v_pk_mul_f32 v[40:41], v[40:41], v[60:61] op_sel_hi:[1,0]
	v_pk_mul_f32 v[56:57], v[52:53], v[56:57]
	v_pk_mul_f32 v[42:43], v[42:43], v[60:61] op_sel_hi:[1,0]
	v_cvt_pk_bf16_f32 v66, v56, v57
	v_pk_mul_f32 v[56:57], v[58:59], v[62:63] op_sel_hi:[1,0]
	v_mul_f32_e32 v58, 0x4b800000, v64
	v_cndmask_b32_e32 v58, v64, v58, vcc
	v_rsq_f32_e32 v58, v58
	v_pk_mul_f32 v[56:57], v[54:55], v[56:57]
	v_pk_mul_f32 v[36:37], v[36:37], v[62:63] op_sel_hi:[1,0]
	v_cvt_pk_bf16_f32 v67, v56, v57
	v_mul_f32_e32 v59, 0x45800000, v58
	v_cndmask_b32_e32 v58, v58, v59, vcc
	v_pk_mul_f32 v[48:49], v[48:49], v[58:59] op_sel_hi:[1,0]
	v_pk_mul_f32 v[50:51], v[50:51], v[58:59] op_sel_hi:[1,0]
	v_add_co_u32_e64 v56, s[38:39], s46, v70
	v_pk_mul_f32 v[48:49], v[52:53], v[48:49]
	v_pk_mul_f32 v[50:51], v[54:55], v[50:51]
	v_addc_co_u32_e64 v57, s[38:39], 0, v71, s[38:39]
	v_cvt_pk_bf16_f32 v48, v48, v49
	v_cvt_pk_bf16_f32 v49, v50, v51
	global_store_dwordx2 v[56:57], v[66:67], off
	global_store_dwordx2 v[56:57], v[48:49], off offset:2048
	v_mov_b32_e32 v48, v104
	v_mov_b32_e32 v49, v105
	v_mov_b32_e32 v50, v106
	v_mov_b32_e32 v51, v107
	v_pk_mul_f32 v[38:39], v[38:39], v[62:63] op_sel_hi:[1,0]
	v_pk_mul_f32 v[32:33], v[32:33], v[58:59] op_sel_hi:[1,0]
	v_pk_mul_f32 v[34:35], v[34:35], v[58:59] op_sel_hi:[1,0]
	v_pk_mul_f32 v[24:25], v[24:25], v[60:61] op_sel_hi:[1,0]
	v_pk_mul_f32 v[26:27], v[26:27], v[60:61] op_sel_hi:[1,0]
	v_pk_mul_f32 v[20:21], v[20:21], v[62:63] op_sel_hi:[1,0]
	v_pk_mul_f32 v[22:23], v[22:23], v[62:63] op_sel_hi:[1,0]
	v_pk_mul_f32 v[16:17], v[16:17], v[58:59] op_sel_hi:[1,0]
	v_pk_mul_f32 v[18:19], v[18:19], v[58:59] op_sel_hi:[1,0]
	v_pk_mul_f32 v[44:45], v[48:49], v[44:45]
	v_pk_mul_f32 v[46:47], v[50:51], v[46:47]
	v_pk_mul_f32 v[40:41], v[48:49], v[40:41]
	v_pk_mul_f32 v[42:43], v[50:51], v[42:43]
	v_pk_mul_f32 v[36:37], v[48:49], v[36:37]
	v_pk_mul_f32 v[38:39], v[50:51], v[38:39]
	v_pk_mul_f32 v[32:33], v[48:49], v[32:33]
	v_pk_mul_f32 v[34:35], v[50:51], v[34:35]
	v_cvt_pk_bf16_f32 v44, v44, v45
	v_cvt_pk_bf16_f32 v45, v46, v47
	v_cvt_pk_bf16_f32 v40, v40, v41
	v_cvt_pk_bf16_f32 v41, v42, v43
	v_cvt_pk_bf16_f32 v36, v36, v37
	v_cvt_pk_bf16_f32 v37, v38, v39
	v_cvt_pk_bf16_f32 v32, v32, v33
	v_cvt_pk_bf16_f32 v33, v34, v35
	global_store_dwordx2 v[70:71], v[44:45], off offset:512
	global_store_dwordx2 v[70:71], v[40:41], off offset:2560
	global_store_dwordx2 v[56:57], v[36:37], off offset:512
	global_store_dwordx2 v[56:57], v[32:33], off offset:2560
	v_mov_b32_e32 v32, v108
	v_mov_b32_e32 v33, v109
	v_mov_b32_e32 v34, v110
	v_mov_b32_e32 v35, v111
	v_pk_mul_f32 v[28:29], v[28:29], v[32:33]
	v_pk_mul_f32 v[30:31], v[30:31], v[34:35]
	v_pk_mul_f32 v[24:25], v[24:25], v[32:33]
	v_pk_mul_f32 v[26:27], v[26:27], v[34:35]
	v_pk_mul_f32 v[20:21], v[20:21], v[32:33]
	v_pk_mul_f32 v[22:23], v[22:23], v[34:35]
	v_pk_mul_f32 v[16:17], v[16:17], v[32:33]
	v_pk_mul_f32 v[18:19], v[18:19], v[34:35]
	v_cvt_pk_bf16_f32 v28, v28, v29
	v_cvt_pk_bf16_f32 v29, v30, v31
	v_cvt_pk_bf16_f32 v24, v24, v25
	v_cvt_pk_bf16_f32 v25, v26, v27
	v_cvt_pk_bf16_f32 v20, v20, v21
	v_cvt_pk_bf16_f32 v21, v22, v23
	v_cvt_pk_bf16_f32 v16, v16, v17
	v_cvt_pk_bf16_f32 v17, v18, v19
	global_store_dwordx2 v[70:71], v[28:29], off offset:1024
	global_store_dwordx2 v[70:71], v[24:25], off offset:3072
	global_store_dwordx2 v[56:57], v[20:21], off offset:1024
	global_store_dwordx2 v[56:57], v[16:17], off offset:3072
	v_mov_b32_e32 v16, v112
	v_mov_b32_e32 v17, v113
	v_mov_b32_e32 v18, v114
	v_mov_b32_e32 v19, v115
	v_pk_mul_f32 v[0:1], v[0:1], v[16:17]
	v_pk_mul_f32 v[2:3], v[2:3], v[18:19]
	v_cvt_pk_bf16_f32 v0, v0, v1
	v_cvt_pk_bf16_f32 v1, v2, v3
	global_store_dwordx2 v[70:71], v[0:1], off offset:1536
	v_pk_mul_f32 v[0:1], v[4:5], v[60:61] op_sel_hi:[1,0]
	v_pk_mul_f32 v[2:3], v[6:7], v[60:61] op_sel_hi:[1,0]
	v_pk_mul_f32 v[0:1], v[0:1], v[16:17]
	v_pk_mul_f32 v[2:3], v[2:3], v[18:19]
	v_cvt_pk_bf16_f32 v0, v0, v1
	v_cvt_pk_bf16_f32 v1, v2, v3
	global_store_dwordx2 v[70:71], v[0:1], off offset:3584
	v_pk_mul_f32 v[0:1], v[12:13], v[62:63] op_sel_hi:[1,0]
	v_pk_mul_f32 v[2:3], v[14:15], v[62:63] op_sel_hi:[1,0]
	v_pk_mul_f32 v[0:1], v[0:1], v[16:17]
	v_pk_mul_f32 v[2:3], v[2:3], v[18:19]
	v_cvt_pk_bf16_f32 v0, v0, v1
	v_cvt_pk_bf16_f32 v1, v2, v3
	global_store_dwordx2 v[56:57], v[0:1], off offset:1536
	v_pk_mul_f32 v[0:1], v[8:9], v[58:59] op_sel_hi:[1,0]
	v_pk_mul_f32 v[2:3], v[10:11], v[58:59] op_sel_hi:[1,0]
	v_pk_mul_f32 v[0:1], v[0:1], v[16:17]
	v_pk_mul_f32 v[2:3], v[2:3], v[18:19]
	v_cvt_pk_bf16_f32 v0, v0, v1
	v_cvt_pk_bf16_f32 v1, v2, v3
	v_lshl_add_u64 v[70:71], v[70:71], 0, s[70:71]
	global_store_dwordx2 v[56:57], v[0:1], off offset:3584
	s_cbranch_scc1 .LBB0_310
